# in-proj GEMM restricted to the 2048 full tiles (8 rounds); narrow columns + meta rows by a hand-written K-split MFMA routine; attention V tile restaged conflict-free for transposed reads
# speedup vs baseline: 1.0334x; 1.0261x over previous
.LBB0_177:
	s_or_b64 exec, exec, s[0:1]
	s_cmpk_lt_i32 s2, 0x800
	s_cselect_b64 s[0:1], -1, 0
	v_readfirstlane_b32 s46, v96
	s_and_b64 vcc, exec, s[0:1]
	s_waitcnt lgkmcnt(0)
	s_barrier
	s_cbranch_vccz .LBB0_179
	s_and_b32 s3, s2, 7
	s_lshl_b32 s3, s3, 3
	s_bfe_u32 s4, s2, 0x30003
	s_add_i32 s4, s4, s3
	s_lshr_b32 s74, s2, 6

.LBB0_182:
	s_mov_b64 s[42:43], 0x80
	s_and_b32 s1, s1, 3
	s_add_i32 m0, s75, 0x18000
	v_lshl_add_u64 v[6:7], v[6:7], 0, s[42:43]
	s_lshl_b32 s5, s0, 13
	s_lshl_b32 s47, s1, 12
	s_waitcnt vmcnt(2)
	s_barrier
	global_load_lds_dwordx4 v[6:7], off
	v_lshl_add_u64 v[4:5], v[4:5], 0, s[42:43]
	s_add_i32 m0, s75, 0x1a000
	s_add_i32 s90, s75, 0x8000
	s_add_i32 s91, s75, 0xa000
	global_load_lds_dwordx4 v[4:5], off
	v_lshl_add_u64 v[0:1], v[0:1], 0, s[42:43]
	s_mov_b32 m0, s90
	s_add_u32 s48, s78, 0x80080
	global_load_lds_dwordx4 v[0:1], off
	v_lshl_add_u64 v[0:1], v[2:3], 0, s[42:43]
	s_mov_b32 m0, s91
	s_addc_u32 s49, s79, 0
	global_load_lds_dwordx4 v[0:1], off
	s_add_i32 m0, s75, 0x1c000
	v_lshl_add_u64 v[0:1], s[48:49], 0, v[130:131]
	global_load_lds_dwordx4 v[0:1], off
	v_lshl_add_u64 v[0:1], s[48:49], 0, v[134:135]
	s_add_i32 m0, s75, 0x1e000
	v_and_b32_e32 v2, 15, v96
	global_load_lds_dwordx4 v[0:1], off
	v_lshrrev_b32_e32 v0, 1, v96
	v_and_b32_e32 v3, 24, v0
	v_lshlrev_b32_e32 v0, 6, v2
	v_lshl_or_b32 v4, v3, 1, v0
	v_lshlrev_b32_e32 v0, 2, v96
	v_and_b32_e32 v5, 32, v0
	v_lshlrev_b32_e32 v0, 2, v3
	v_mov_b32_e32 v1, v131
	v_lshl_add_u64 v[136:137], s[12:13], 0, v[0:1]
	v_lshlrev_b32_e32 v1, 15, v8
	v_and_b32_e32 v1, 0xffff0000, v1
	v_lshl_or_b32 v152, s0, 6, v2
	v_lshl_add_u32 v1, v9, 12, v1
	v_and_b32_e32 v2, 1, v8
	v_lshl_or_b32 v1, v2, 6, v1
	v_lshl_add_u32 v138, v10, 1, v1
	v_lshlrev_b32_e32 v1, 15, v11
	s_cmpk_lt_u32 s46, 0x100
	v_and_b32_e32 v1, 0xffff0000, v1
	v_bitop3_b32 v153, s47, v4, v5 bitop3:0xf6
	s_waitcnt vmcnt(6)
	s_cselect_b64 s[46:47], -1, 0
	s_cmp_eq_u32 s1, 0
	v_lshl_add_u32 v1, v12, 12, v1
	v_and_b32_e32 v2, 1, v11
	v_bitop3_b32 v0, v4, s5, v5 bitop3:0xde
	s_cselect_b64 s[48:49], -1, 0
	v_lshl_or_b32 v1, v2, 6, v1
	s_add_i32 s92, 0, 0x10000
	s_add_i32 s93, 0, 0x14000
	v_lshl_or_b32 v155, s1, 5, v3
	v_mov_b32_e32 v139, v131
	v_lshl_add_u32 v140, v13, 1, v1
	v_mov_b32_e32 v141, v131
	v_mov_b64_e32 v[142:143], 0x800
	v_mov_b64_e32 v[144:145], 0x7ff
	v_add_u32_e32 v156, s92, v153
	v_add_u32_e32 v157, s93, v153
	v_add_u32_e32 v158, 0, v0
	s_mov_b64 s[50:51], 0x4000
	s_mov_b64 s[52:53], 0x4800
	s_mov_b64 s[54:55], 0x5000
	s_mov_b64 s[56:57], 0x5800
	s_mov_b64 s[58:59], 0x200000
	s_mov_b64 s[60:61], 0x240000
	s_mov_b64 s[62:63], 0x280000
	s_mov_b64 s[64:65], 0x2c0000
	s_barrier
	s_branch .LBB0_185

.LBB0_185:
	s_add_i32 s89, s89, 1
	s_mul_i32 s0, s89, s35
	s_mul_hi_u32 s1, s89, s30
	s_add_i32 s1, s1, s0
	s_mul_i32 s0, s89, s30
	s_add_u32 s70, s0, s2
	s_addc_u32 s71, s1, s84
	v_cmp_gt_i64_e32 vcc, s[70:71], v[144:145]
	v_cmp_lt_i64_e64 s[0:1], s[70:71], v[142:143]
	s_cbranch_vccnz .LBB0_191
	s_and_b32 s66, s70, 7
	s_lshl_b32 s66, s66, 3
	s_bfe_u32 s68, s70, 0x30003
	s_add_i32 s68, s68, s66
	s_lshr_b32 s66, s70, 6

.LBB0_237:
	s_waitcnt vmcnt(0)
	s_waitcnt vmcnt(0)
	v_and_b32_e32 v148, 63, v154
	v_lshrrev_b32_e32 v149, 6, v154
	v_and_b32_e32 v150, 31, v148
	v_lshrrev_b32_e32 v151, 5, v148
	v_lshlrev_b32_e32 v152, 6, v151
	v_lshl_or_b32 v152, v149, 9, v152
	s_add_u32 s50, s28, 0x4100000
	s_addc_u32 s51, s29, 0
	s_add_u32 s52, s28, 0x17400000
	s_addc_u32 s53, s29, 0
	s_add_u32 s54, s28, 0x7000000
	s_addc_u32 s55, s29, 0
	v_lshlrev_b32_e32 v153, 4, v148
	v_lshl_add_u32 v153, v149, 12, v153
	v_lshrrev_b32_e32 v157, 1, v149
	v_lshlrev_b32_e32 v156, 4, v148
	v_lshl_add_u32 v156, v157, 10, v156
	v_and_b32_e32 v159, 1, v149
	v_lshl_add_u32 v156, v159, 3, v156
	v_lshlrev_b32_e32 v158, 1, v159
	v_lshl_add_u32 v158, v157, 3, v158
	v_lshl_add_u32 v158, v151, 2, v158
	s_mov_b32 s58, 0
	s_sub_i32 s48, s2, 0xab
	s_cmp_lt_u32 s2, 0xab
	s_cselect_b32 s59, 1, 0
	s_movk_i32 s60, 0x55
	s_cselect_b32 s60, 0xab, s60
	s_movk_i32 s61, 0x100
	s_cselect_b32 s61, 0x201, s61
	s_cselect_b32 s48, s2, s48
	s_lshl_b32 s56, s48, 5
	s_cmp_eq_u32 s59, 1
	s_cselect_b32 s57, s56, 0x4000
	s_cselect_b32 s56, 0x2000, s56
	v_add_u32_e32 v144, s57, v150
	v_lshl_add_u32 v144, v144, 12, v152
	v_add_u32_e32 v146, s56, v150
	v_lshl_add_u32 v146, v146, 12, v152
	s_cbranch_scc0 .Lsl_first_meta
	global_load_dwordx4 v[64:67], v146, s[50:51]
	global_load_dwordx4 v[68:71], v146, s[50:51] offset:16
	global_load_dwordx4 v[72:75], v146, s[50:51] offset:32
	global_load_dwordx4 v[76:79], v146, s[50:51] offset:48
	global_load_dwordx4 v[80:83], v146, s[50:51] offset:128
	global_load_dwordx4 v[84:87], v146, s[50:51] offset:144
	global_load_dwordx4 v[88:91], v146, s[50:51] offset:160
	global_load_dwordx4 v[92:95], v146, s[50:51] offset:176
	global_load_dwordx4 v[96:99], v146, s[50:51] offset:256
	global_load_dwordx4 v[100:103], v146, s[50:51] offset:272
	global_load_dwordx4 v[104:107], v146, s[50:51] offset:288
	global_load_dwordx4 v[108:111], v146, s[50:51] offset:304
	global_load_dwordx4 v[112:115], v146, s[50:51] offset:384
	global_load_dwordx4 v[116:119], v146, s[50:51] offset:400
	global_load_dwordx4 v[120:123], v146, s[50:51] offset:416
	global_load_dwordx4 v[124:127], v146, s[50:51] offset:432
	global_load_dwordx4 v[0:3], v144, s[28:29]
	global_load_dwordx4 v[4:7], v144, s[28:29] offset:16
	global_load_dwordx4 v[8:11], v144, s[28:29] offset:32
	global_load_dwordx4 v[12:15], v144, s[28:29] offset:48
	global_load_dwordx4 v[16:19], v144, s[28:29] offset:128
	global_load_dwordx4 v[20:23], v144, s[28:29] offset:144
	global_load_dwordx4 v[24:27], v144, s[28:29] offset:160
	global_load_dwordx4 v[28:31], v144, s[28:29] offset:176
	global_load_dwordx4 v[32:35], v144, s[28:29] offset:256
	global_load_dwordx4 v[36:39], v144, s[28:29] offset:272
	global_load_dwordx4 v[40:43], v144, s[28:29] offset:288
	global_load_dwordx4 v[44:47], v144, s[28:29] offset:304
	global_load_dwordx4 v[48:51], v144, s[28:29] offset:384
	global_load_dwordx4 v[52:55], v144, s[28:29] offset:400
	global_load_dwordx4 v[56:59], v144, s[28:29] offset:416
	global_load_dwordx4 v[60:63], v144, s[28:29] offset:432
	s_branch .Lsl_next
.Lsl_first_meta:
	global_load_dwordx4 v[0:3], v144, s[28:29]
	global_load_dwordx4 v[4:7], v144, s[28:29] offset:16
	global_load_dwordx4 v[8:11], v144, s[28:29] offset:32
	global_load_dwordx4 v[12:15], v144, s[28:29] offset:48
	global_load_dwordx4 v[16:19], v144, s[28:29] offset:128
	global_load_dwordx4 v[20:23], v144, s[28:29] offset:144
	global_load_dwordx4 v[24:27], v144, s[28:29] offset:160
	global_load_dwordx4 v[28:31], v144, s[28:29] offset:176
	global_load_dwordx4 v[32:35], v144, s[28:29] offset:256
	global_load_dwordx4 v[36:39], v144, s[28:29] offset:272
	global_load_dwordx4 v[40:43], v144, s[28:29] offset:288
	global_load_dwordx4 v[44:47], v144, s[28:29] offset:304
	global_load_dwordx4 v[48:51], v144, s[28:29] offset:384
	global_load_dwordx4 v[52:55], v144, s[28:29] offset:400
	global_load_dwordx4 v[56:59], v144, s[28:29] offset:416
	global_load_dwordx4 v[60:63], v144, s[28:29] offset:432
	global_load_dwordx4 v[64:67], v146, s[50:51]
	global_load_dwordx4 v[68:71], v146, s[50:51] offset:16
	global_load_dwordx4 v[72:75], v146, s[50:51] offset:32
	global_load_dwordx4 v[76:79], v146, s[50:51] offset:48
	global_load_dwordx4 v[80:83], v146, s[50:51] offset:128
	global_load_dwordx4 v[84:87], v146, s[50:51] offset:144
	global_load_dwordx4 v[88:91], v146, s[50:51] offset:160
	global_load_dwordx4 v[92:95], v146, s[50:51] offset:176
	global_load_dwordx4 v[96:99], v146, s[50:51] offset:256
	global_load_dwordx4 v[100:103], v146, s[50:51] offset:272
	global_load_dwordx4 v[104:107], v146, s[50:51] offset:288
	global_load_dwordx4 v[108:111], v146, s[50:51] offset:304
	global_load_dwordx4 v[112:115], v146, s[50:51] offset:384
	global_load_dwordx4 v[116:119], v146, s[50:51] offset:400
	global_load_dwordx4 v[120:123], v146, s[50:51] offset:416
	global_load_dwordx4 v[124:127], v146, s[50:51] offset:432
	s_branch .Lsl_next
.Lsl_loop:
	s_waitcnt vmcnt(12)
	v_mfma_f32_32x32x16_bf16 v[128:143], v[64:67], v[0:3], 0
	v_mfma_f32_32x32x16_bf16 v[128:143], v[68:71], v[4:7], v[128:143]
	v_mfma_f32_32x32x16_bf16 v[128:143], v[72:75], v[8:11], v[128:143]
	v_mfma_f32_32x32x16_bf16 v[128:143], v[76:79], v[12:15], v[128:143]
	s_waitcnt vmcnt(8)
	v_mfma_f32_32x32x16_bf16 v[128:143], v[80:83], v[16:19], v[128:143]
	v_mfma_f32_32x32x16_bf16 v[128:143], v[84:87], v[20:23], v[128:143]
	v_mfma_f32_32x32x16_bf16 v[128:143], v[88:91], v[24:27], v[128:143]
	v_mfma_f32_32x32x16_bf16 v[128:143], v[92:95], v[28:31], v[128:143]
	s_waitcnt vmcnt(4)
	v_mfma_f32_32x32x16_bf16 v[128:143], v[96:99], v[32:35], v[128:143]
	v_mfma_f32_32x32x16_bf16 v[128:143], v[100:103], v[36:39], v[128:143]
	v_mfma_f32_32x32x16_bf16 v[128:143], v[104:107], v[40:43], v[128:143]
	v_mfma_f32_32x32x16_bf16 v[128:143], v[108:111], v[44:47], v[128:143]
	s_waitcnt vmcnt(0)
	v_mfma_f32_32x32x16_bf16 v[128:143], v[112:115], v[48:51], v[128:143]
	v_mfma_f32_32x32x16_bf16 v[128:143], v[116:119], v[52:55], v[128:143]
	v_mfma_f32_32x32x16_bf16 v[128:143], v[120:123], v[56:59], v[128:143]
	v_mfma_f32_32x32x16_bf16 v[128:143], v[124:127], v[60:63], v[128:143]
	s_add_i32 s48, s46, s60
	s_cmp_lt_u32 s48, s61
	s_cbranch_scc0 .Lsl_reduce
	s_lshl_b32 s56, s48, 5
	v_add_u32_e32 v145, s56, v150
	v_lshl_add_u32 v145, v145, 12, v152
	s_cmp_eq_u32 s59, 1
	s_cbranch_scc0 .Lsl_next_meta
	global_load_dwordx4 v[0:3], v145, s[28:29]
	global_load_dwordx4 v[4:7], v145, s[28:29] offset:16
	global_load_dwordx4 v[8:11], v145, s[28:29] offset:32
	global_load_dwordx4 v[12:15], v145, s[28:29] offset:48
	global_load_dwordx4 v[16:19], v145, s[28:29] offset:128
	global_load_dwordx4 v[20:23], v145, s[28:29] offset:144
	global_load_dwordx4 v[24:27], v145, s[28:29] offset:160
	global_load_dwordx4 v[28:31], v145, s[28:29] offset:176
	global_load_dwordx4 v[32:35], v145, s[28:29] offset:256
	global_load_dwordx4 v[36:39], v145, s[28:29] offset:272
	global_load_dwordx4 v[40:43], v145, s[28:29] offset:288
	global_load_dwordx4 v[44:47], v145, s[28:29] offset:304
	global_load_dwordx4 v[48:51], v145, s[28:29] offset:384
	global_load_dwordx4 v[52:55], v145, s[28:29] offset:400
	global_load_dwordx4 v[56:59], v145, s[28:29] offset:416
	global_load_dwordx4 v[60:63], v145, s[28:29] offset:432
	s_branch .Lsl_reduce
.Lsl_next_meta:
	global_load_dwordx4 v[64:67], v145, s[50:51]
	global_load_dwordx4 v[68:71], v145, s[50:51] offset:16
	global_load_dwordx4 v[72:75], v145, s[50:51] offset:32
	global_load_dwordx4 v[76:79], v145, s[50:51] offset:48
	global_load_dwordx4 v[80:83], v145, s[50:51] offset:128
	global_load_dwordx4 v[84:87], v145, s[50:51] offset:144
	global_load_dwordx4 v[88:91], v145, s[50:51] offset:160
	global_load_dwordx4 v[92:95], v145, s[50:51] offset:176
	global_load_dwordx4 v[96:99], v145, s[50:51] offset:256
	global_load_dwordx4 v[100:103], v145, s[50:51] offset:272
	global_load_dwordx4 v[104:107], v145, s[50:51] offset:288
	global_load_dwordx4 v[108:111], v145, s[50:51] offset:304
	global_load_dwordx4 v[112:115], v145, s[50:51] offset:384
	global_load_dwordx4 v[116:119], v145, s[50:51] offset:400
	global_load_dwordx4 v[120:123], v145, s[50:51] offset:416
	global_load_dwordx4 v[124:127], v145, s[50:51] offset:432
.Lsl_reduce:
	s_nop 15
	v_add_u32_e32 v160, s58, v153
	ds_write_b128 v160, v[128:131]
	ds_write_b128 v160, v[132:135] offset:1024
	ds_write_b128 v160, v[136:139] offset:2048
	ds_write_b128 v160, v[140:143] offset:3072
	s_waitcnt lgkmcnt(0)
	s_barrier
	v_add_u32_e32 v161, s58, v156
	ds_read_b64 v[162:163], v161
	ds_read_b64 v[164:165], v161 offset:4096
	ds_read_b64 v[166:167], v161 offset:8192
	ds_read_b64 v[168:169], v161 offset:12288
	ds_read_b64 v[170:171], v161 offset:16384
	ds_read_b64 v[172:173], v161 offset:20480
	ds_read_b64 v[174:175], v161 offset:24576
	ds_read_b64 v[176:177], v161 offset:28672
	s_xor_b32 s58, s58, 0x8000
	s_waitcnt lgkmcnt(0)
	v_add_f32_e32 v162, v162, v164
	v_add_f32_e32 v163, v163, v165
	v_add_f32_e32 v162, v162, v166
	v_add_f32_e32 v163, v163, v167
	v_add_f32_e32 v162, v162, v168
	v_add_f32_e32 v163, v163, v169
	v_add_f32_e32 v162, v162, v170
	v_add_f32_e32 v163, v163, v171
	v_add_f32_e32 v162, v162, v172
	v_add_f32_e32 v163, v163, v173
	v_add_f32_e32 v162, v162, v174
	v_add_f32_e32 v163, v163, v175
	v_add_f32_e32 v162, v162, v176
	v_add_f32_e32 v163, v163, v177
	s_cmp_eq_u32 s59, 1
	s_cbranch_scc0 .Lsl_epi_meta
	s_lshl_b32 s56, s46, 5
	v_add_u32_e32 v164, s56, v150
	v_lshlrev_b32_e32 v164, 7, v164
	v_lshl_add_u32 v164, v158, 2, v164
	global_store_dwordx2 v164, v[162:163], s[52:53]
	s_branch .Lsl_next
.Lsl_epi_meta:
	s_lshr_b32 s57, s46, 3
	s_and_b32 s57, s57, 12
	s_cmp_eq_u32 s57, 12
	s_cbranch_scc0 .Lsl_nogate
	v_mul_f32_e32 v164, 0xbfb8aa3b, v162
	v_mul_f32_e32 v165, 0xbfb8aa3b, v163
	v_exp_f32_e32 v164, v164
	v_exp_f32_e32 v165, v165
	s_nop 0
	v_add_f32_e32 v164, 1.0, v164
	v_add_f32_e32 v165, 1.0, v165
	v_rcp_f32_e32 v164, v164
	v_rcp_f32_e32 v165, v165
	s_nop 0
	v_mul_f32_e32 v162, v162, v164
	v_mul_f32_e32 v163, v163, v165
.Lsl_nogate:
	v_cvt_pk_bf16_f32 v162, v162, v163
	v_add_u32_e32 v164, 0x4000, v150
	v_lshlrev_b32_e32 v164, 14, v164
	s_lshl_b32 s56, s46, 6
	v_lshl_add_u32 v165, v158, 1, s56
	v_add_u32_e32 v164, v164, v165
	global_store_dword v164, v162, s[54:55]
.Lsl_next:
	s_mov_b32 s46, s48
	s_cmp_lt_u32 s46, s61
	s_cbranch_scc1 .Lsl_loop
	s_waitcnt vmcnt(0)
	s_barrier
	s_mov_b64 s[0:1], exec
	v_readlane_b32 s4, v246, 0
	v_readlane_b32 s5, v246, 1
	s_and_b64 s[4:5], s[0:1], s[4:5]
	s_xor_b64 s[0:1], s[4:5], s[0:1]
	s_mov_b64 exec, s[4:5]
	s_cbranch_execz .LBB0_290
	s_add_i32 s3, 0, 0x261e0
	v_mov_b32_e32 v0, s3
	s_waitcnt vmcnt(0) expcnt(0) lgkmcnt(0)
	ds_read_b32 v2, v0
	s_add_i32 s3, 0, 0x261e4
	v_mov_b32_e32 v0, s3
	ds_read_b32 v0, v0
	s_waitcnt lgkmcnt(1)
	v_cmp_ne_u32_e32 vcc, 0, v2
	s_cbranch_vccnz .LBB0_253
	s_add_u32 s4, s28, 0x1dc10200
	s_addc_u32 s5, s29, 0
	s_add_u32 s14, s28, 0x1dc10400
	s_addc_u32 s15, s29, 0
	s_add_u32 s42, s28, 0x1dc10500
	s_addc_u32 s43, s29, 0
	s_add_u32 s46, s28, 0x1dc10600
	s_addc_u32 s47, s29, 0
	s_add_u32 s48, s28, 0x1dc10700
	s_addc_u32 s49, s29, 0
	s_add_u32 s50, s28, 0x1dc10800
	s_addc_u32 s51, s29, 0
	s_add_u32 s52, s28, 0x1dc10900
	s_addc_u32 s53, s29, 0
	s_add_u32 s54, s28, 0x1dc10a00
	s_addc_u32 s55, s29, 0
	s_add_u32 s56, s28, 0x1dc10b00
	s_addc_u32 s57, s29, 0
	s_add_u32 s58, s28, 0x1dc10c00
	s_addc_u32 s59, s29, 0
	s_add_u32 s60, s28, 0x1dc10d00
	s_addc_u32 s61, s29, 0
	s_add_u32 s62, s28, 0x1dc10e00
	s_addc_u32 s63, s29, 0
	s_add_u32 s64, s28, 0x1dc10f00
	s_addc_u32 s65, s29, 0
	s_add_u32 s66, s28, 0x1dc11000
	s_addc_u32 s67, s29, 0
	s_add_u32 s68, s28, 0x1dc11100
	s_addc_u32 s69, s29, 0
	s_add_u32 s70, s28, 0x1dc11200
	s_addc_u32 s71, s29, 0
	s_mul_i32 s3, s31, s7
	s_add_u32 s72, s28, 0x1dc11300
	s_mul_i32 s3, s3, s30
	s_addc_u32 s73, s29, 0
	s_mov_b32 s33, 1
	v_mov_b32_e32 v16, 0
	s_branch .LBB0_241

.LBB0_500:
	s_nop 0
	v_readfirstlane_b32 s0, v154
	s_ashr_i32 s98, s0, 6
	v_and_b32_e32 v185, 63, v154
	s_cmp_gt_i32 s99, 63
	s_mov_b64 s[0:1], -1
	s_cbranch_scc0 .LBB0_552
	v_and_b32_e32 v247, 3, v154
	v_lshlrev_b32_e32 v247, 3, v247
	v_bfe_u32 v249, v154, 2, 2
	v_lshl_or_b32 v247, v249, 6, v247
	v_bfe_u32 v249, v154, 4, 1
	v_lshl_or_b32 v247, v249, 5, v247
	v_bfe_u32 v249, v154, 5, 1
	v_lshl_or_b32 v247, v249, 8, v247
	v_and_b32_e32 v248, 3, v154
	v_lshlrev_b32_e32 v248, 4, v248
	v_bfe_u32 v249, v154, 2, 2
	v_lshl_or_b32 v248, v249, 9, v248
	v_bfe_u32 v249, v154, 4, 3
	v_lshl_or_b32 v248, v249, 6, v248
	v_bfe_u32 v249, v154, 7, 2
	v_lshl_or_b32 v248, v249, 11, v248
	s_sub_i32 s0, s99, 64
	s_not_b32 s1, s0
	s_lshl_b32 s1, s1, 2
	s_and_b32 s59, s1, 0x700
	s_lshl_b32 s1, s0, 8
	s_and_b32 s33, s1, 0x3800
	v_ashrrev_i32_e32 v48, 1, v154
	s_or_b32 s12, s59, s33
	v_ashrrev_i32_e32 v49, 31, v48
	v_lshl_add_u64 v[0:1], s[12:13], 0, v[48:49]
	s_lshl_b32 s0, s0, 7
	v_lshlrev_b64 v[0:1], 14, v[0:1]
	s_and_b32 s0, s0, 0x380
	v_lshl_add_u64 v[0:1], s[10:11], 0, v[0:1]
	s_lshl_b32 s14, s0, 1
	s_mov_b32 s15, s13
	v_and_b32_e32 v2, 1, v154
	v_lshl_add_u64 v[0:1], v[0:1], 0, s[14:15]
	v_lshlrev_b32_e32 v50, 7, v2
	v_mov_b32_e32 v51, v129
	v_lshl_add_u64 v[0:1], v[0:1], 0, v[50:51]
	s_mov_b64 s[0:1], 0x3800
	v_lshl_add_u64 v[2:3], v[0:1], 0, s[0:1]
	v_add_co_u32_e32 v0, vcc, s63, v0
	s_and_b32 s0, s99, 63
	s_nop 0
	v_addc_co_u32_e32 v1, vcc, 0, v1, vcc
	global_load_dwordx4 v[24:27], v[2:3], off offset:32
	global_load_dwordx4 v[32:35], v[2:3], off offset:16
	global_load_dwordx4 v[36:39], v[0:1], off offset:2048
	global_load_dwordx4 v[16:19], v[2:3], off offset:112
	global_load_dwordx4 v[20:23], v[2:3], off offset:96
	global_load_dwordx4 v[28:31], v[2:3], off offset:80
	global_load_dwordx4 v[44:47], v[2:3], off offset:48
	global_load_dwordx4 v[40:43], v[2:3], off offset:64
	s_mulk_i32 s0, 0x840
	s_add_i32 s58, s59, 0x10f
	s_lshl_b32 s57, s0, 2
	v_mov_b32_e32 v128, v129
	s_add_u32 s4, s70, s57
	v_mov_b32_e32 v130, v129
	v_mov_b32_e32 v131, v129
	v_lshlrev_b32_e32 v116, 2, v154
	v_mov_b64_e32 v[112:113], v[128:129]
	s_addc_u32 s5, s71, 0
	v_cmp_gt_i32_e64 s[0:1], 16, v154
	s_and_b32 s56, s58, 0xf00
	v_ashrrev_i32_e32 v117, 31, v116
	v_mov_b64_e32 v[114:115], v[130:131]
	s_and_saveexec_b64 s[54:55], s[0:1]
	s_cbranch_execz .LBB0_503
	s_lshl_b32 s3, s56, 2
	s_add_u32 vcc_lo, s4, s3
	s_addc_u32 vcc_hi, s5, 0
	v_lshl_add_u64 v[0:1], v[116:117], 2, vcc
	global_load_dwordx4 v[112:115], v[0:1], off
.LBB0_503:
	s_or_b64 exec, exec, s[54:55]
	s_lshl_b32 s3, s98, 5
	s_ashr_i32 s54, s3, 31
	s_add_u32 s12, s3, s12
	v_and_b32_e32 v186, 31, v154
	s_addc_u32 s54, s54, 0
	s_waitcnt vmcnt(8)
	v_or_b32_e32 v156, s12, v186
	v_mov_b32_e32 v157, s54
	s_add_u32 s54, s85, s57
	v_lshlrev_b64 v[2:3], 14, v[156:157]
	v_lshrrev_b32_e32 v121, 5, v185
	s_addc_u32 s55, s86, 0
	s_add_i32 s33, s33, -16
	v_lshl_add_u64 v[2:3], s[10:11], 0, v[2:3]
	s_add_u32 vcc_lo, s10, s14
	v_lshlrev_b32_e32 v187, 4, v154
	v_lshl_add_u64 v[2:3], v[2:3], 0, s[14:15]
	v_lshlrev_b32_e32 v162, 4, v121
	v_mov_b32_e32 v163, v129
	s_addc_u32 vcc_hi, s11, 0
	v_and_b32_e32 v128, 0xf0, v187
	v_lshl_add_u64 v[2:3], v[2:3], 0, v[162:163]
	v_lshl_add_u64 v[160:161], vcc, 0, v[128:129]
	v_ashrrev_i32_e32 v119, 4, v154
	v_lshl_add_u64 v[52:53], v[2:3], 0, s[36:37]
	v_add_co_u32_e32 v2, vcc, s65, v2
	v_add_u32_e32 v1, s56, v119
	s_nop 0
	v_addc_co_u32_e32 v3, vcc, 0, v3, vcc
	v_mov_b32_e32 v6, s33
	v_cmp_lt_i32_e32 vcc, 15, v1
	v_min_i32_e32 v0, 0x80f, v1
	global_load_dwordx4 v[80:83], v[2:3], off
	global_load_dwordx4 v[86:89], v[52:53], off offset:224
	v_cndmask_b32_e32 v1, v179, v6, vcc
	v_add_u32_e32 v2, v1, v0
	v_ashrrev_i32_e32 v3, 31, v2
	v_lshlrev_b64 v[2:3], 14, v[2:3]
	v_lshl_add_u64 v[2:3], v[160:161], 0, v[2:3]
	v_add_co_u32_e32 v4, vcc, s65, v2
	v_ashrrev_i32_e32 v1, 31, v0
	s_nop 0
	v_addc_co_u32_e32 v5, vcc, 0, v3, vcc
	v_add_co_u32_e32 v2, vcc, s63, v2
	v_lshl_add_u64 v[0:1], v[0:1], 2, s[54:55]
	s_nop 0
	v_addc_co_u32_e32 v3, vcc, 0, v3, vcc
	global_load_dwordx4 v[96:99], v[52:53], off offset:160
	global_load_dwordx4 v[100:103], v[52:53], off offset:192
	global_load_dwordx4 v[12:15], v[4:5], off offset:2048
	global_load_dwordx4 v[8:11], v[2:3], off
	v_add_u32_e32 v2, 0x200, v154
	v_ashrrev_i32_e32 v189, 4, v2
	v_add_u32_e32 v3, s56, v189
	v_cmp_lt_i32_e32 vcc, 15, v3
	v_min_i32_e32 v2, 0x80f, v3
	v_mul_lo_u32 v48, v48, s66
	v_cndmask_b32_e32 v3, v179, v6, vcc
	v_add_u32_e32 v4, v3, v2
	v_ashrrev_i32_e32 v5, 31, v4
	v_lshlrev_b64 v[4:5], 14, v[4:5]
	v_lshl_add_u64 v[54:55], v[160:161], 0, v[4:5]
	v_add_co_u32_e32 v4, vcc, s65, v54
	v_ashrrev_i32_e32 v3, 31, v2
	s_nop 0
	v_addc_co_u32_e32 v5, vcc, 0, v55, vcc
	global_load_dword v120, v[0:1], off
	s_nop 0
	global_load_dwordx4 v[4:7], v[4:5], off offset:2048
	v_add_co_u32_e32 v0, vcc, s63, v54
	v_add3_u32 v48, s67, v48, v50
	s_nop 0
	v_addc_co_u32_e32 v1, vcc, 0, v55, vcc
	v_lshl_add_u64 v[54:55], v[2:3], 2, s[54:55]
	global_load_dwordx4 v[0:3], v[0:1], off
	s_nop 0
	global_load_dword v118, v[54:55], off
	global_load_dwordx4 v[172:175], v[52:53], off offset:32
	global_load_dwordx4 v[164:167], v[52:53], off offset:64
	global_load_dwordx4 v[148:151], v[52:53], off offset:96
	global_load_dwordx4 v[140:143], v[52:53], off offset:128
	s_waitcnt vmcnt(19)
	ds_write2_b64 v48, v[36:37], v[38:39] offset1:1
	ds_write2_b64 v48, v[32:33], v[34:35] offset0:2 offset1:3
	ds_write2_b64 v48, v[24:25], v[26:27] offset0:4 offset1:5
	s_waitcnt vmcnt(15)
	ds_write2_b64 v48, v[44:45], v[46:47] offset0:6 offset1:7
	s_waitcnt vmcnt(14)
	ds_write2_b64 v48, v[40:41], v[42:43] offset0:8 offset1:9
	ds_write2_b64 v48, v[28:29], v[30:31] offset0:10 offset1:11
	ds_write2_b64 v48, v[20:21], v[22:23] offset0:12 offset1:13
	ds_write2_b64 v48, v[16:17], v[18:19] offset0:14 offset1:15
	v_and_b32_e32 v16, 32, v185
	v_add_u32_e32 v16, 0, v16
	v_add_u32_e32 v16, 0x25e00, v16
	ds_read_b128 v[76:79], v16
	ds_read_b128 v[72:75], v16 offset:16
	ds_read_b128 v[68:71], v16 offset:64
	ds_read_b128 v[64:67], v16 offset:80
	ds_read_b128 v[60:63], v16 offset:128
	ds_read_b128 v[56:59], v16 offset:144
	ds_read_b128 v[52:55], v16 offset:192
	ds_read_b128 v[48:51], v16 offset:208
	ds_read_b128 v[44:47], v16 offset:256
	ds_read_b128 v[40:43], v16 offset:272
	ds_read_b128 v[36:39], v16 offset:320
	ds_read_b128 v[32:35], v16 offset:336
	ds_read_b128 v[28:31], v16 offset:384
	ds_read_b128 v[24:27], v16 offset:400
	ds_read_b128 v[20:23], v16 offset:448
	ds_read_b128 v[16:19], v16 offset:464
	s_waitcnt vmcnt(13)
	v_and_b32_e32 v177, 0xffff0000, v80
	s_waitcnt vmcnt(12)
	v_and_b32_e32 v85, 0xffff0000, v89
	v_lshlrev_b32_e32 v122, 16, v89
	v_lshlrev_b32_e32 v110, 16, v88
	v_and_b32_e32 v89, 0xffff0000, v88
	v_mov_b32_e32 v88, v85
	v_and_b32_e32 v93, 0xffff0000, v87
	v_mov_b32_e32 v123, v110
	v_pk_mul_f32 v[90:91], v[88:89], v[88:89]
	v_lshlrev_b32_e32 v124, 16, v87
	v_lshlrev_b32_e32 v108, 16, v86
	v_and_b32_e32 v87, 0xffff0000, v86
	v_mov_b32_e32 v86, v93
	v_pk_fma_f32 v[190:191], v[122:123], v[122:123], v[90:91]
	v_mov_b32_e32 v125, v108
	v_pk_mul_f32 v[90:91], v[86:87], v[86:87]
	s_waitcnt vmcnt(10)
	v_and_b32_e32 v131, 0xffff0000, v101
	v_pk_fma_f32 v[192:193], v[124:125], v[124:125], v[90:91]
	v_and_b32_e32 v91, 0xffff0000, v103
	v_lshlrev_b32_e32 v106, 16, v102
	v_and_b32_e32 v95, 0xffff0000, v102
	v_mov_b32_e32 v94, v91
	v_lshlrev_b32_e32 v130, 16, v101
	v_mul_f32_e32 v84, v131, v131
	v_and_b32_e32 v105, 0xffff0000, v100
	v_lshlrev_b32_e32 v126, 16, v103
	v_mov_b32_e32 v127, v106
	v_pk_mul_f32 v[102:103], v[94:95], v[94:95]
	v_pk_fma_f32 v[196:197], v[130:131], v[130:131], v[84:85] op_sel_hi:[1,1,0]
	v_lshlrev_b32_e32 v104, 16, v100
	v_mul_f32_e32 v84, v105, v105
	v_and_b32_e32 v133, 0xffff0000, v99
	v_pk_fma_f32 v[194:195], v[126:127], v[126:127], v[102:103]
	v_pk_fma_f32 v[198:199], v[104:105], v[104:105], v[84:85] op_sel_hi:[1,1,0]
	v_lshlrev_b32_e32 v132, 16, v99
	v_mul_f32_e32 v84, v133, v133
	v_and_b32_e32 v103, 0xffff0000, v98
	v_pk_fma_f32 v[200:201], v[132:133], v[132:133], v[84:85] op_sel_hi:[1,1,0]
	v_lshlrev_b32_e32 v102, 16, v98
	v_mul_f32_e32 v84, v103, v103
	v_and_b32_e32 v135, 0xffff0000, v97
	v_pk_fma_f32 v[202:203], v[102:103], v[102:103], v[84:85] op_sel_hi:[1,1,0]
	v_lshlrev_b32_e32 v134, 16, v97
	v_mul_f32_e32 v84, v135, v135
	v_and_b32_e32 v101, 0xffff0000, v96
	v_pk_fma_f32 v[204:205], v[134:135], v[134:135], v[84:85] op_sel_hi:[1,1,0]
	v_lshlrev_b32_e32 v100, 16, v96
	v_mul_f32_e32 v84, v101, v101
	s_waitcnt vmcnt(0)
	v_and_b32_e32 v137, 0xffff0000, v143
	v_pk_fma_f32 v[206:207], v[100:101], v[100:101], v[84:85] op_sel_hi:[1,1,0]
	v_lshlrev_b32_e32 v136, 16, v143
	v_mul_f32_e32 v84, v137, v137
	v_and_b32_e32 v99, 0xffff0000, v142
	v_pk_fma_f32 v[208:209], v[136:137], v[136:137], v[84:85] op_sel_hi:[1,1,0]
	v_lshlrev_b32_e32 v98, 16, v142
	v_mul_f32_e32 v84, v99, v99
	v_and_b32_e32 v139, 0xffff0000, v141
	v_pk_fma_f32 v[210:211], v[98:99], v[98:99], v[84:85] op_sel_hi:[1,1,0]
	v_lshlrev_b32_e32 v138, 16, v141
	v_mul_f32_e32 v84, v139, v139
	v_and_b32_e32 v97, 0xffff0000, v140
	v_pk_fma_f32 v[212:213], v[138:139], v[138:139], v[84:85] op_sel_hi:[1,1,0]
	v_lshlrev_b32_e32 v96, 16, v140
	v_mul_f32_e32 v84, v97, v97
	v_and_b32_e32 v141, 0xffff0000, v151
	v_pk_fma_f32 v[214:215], v[96:97], v[96:97], v[84:85] op_sel_hi:[1,1,0]
	v_lshlrev_b32_e32 v140, 16, v151
	v_mul_f32_e32 v84, v141, v141
	v_and_b32_e32 v143, 0xffff0000, v150
	v_pk_fma_f32 v[216:217], v[140:141], v[140:141], v[84:85] op_sel_hi:[1,1,0]
	v_lshlrev_b32_e32 v142, 16, v150
	v_mul_f32_e32 v84, v143, v143
	v_and_b32_e32 v145, 0xffff0000, v149
	v_pk_fma_f32 v[218:219], v[142:143], v[142:143], v[84:85] op_sel_hi:[1,1,0]
	v_lshlrev_b32_e32 v144, 16, v149
	v_mul_f32_e32 v84, v145, v145
	v_and_b32_e32 v147, 0xffff0000, v148
	v_pk_fma_f32 v[220:221], v[144:145], v[144:145], v[84:85] op_sel_hi:[1,1,0]
	v_lshlrev_b32_e32 v146, 16, v148
	v_mul_f32_e32 v84, v147, v147
	v_and_b32_e32 v149, 0xffff0000, v167
	v_pk_fma_f32 v[222:223], v[146:147], v[146:147], v[84:85] op_sel_hi:[1,1,0]
	v_lshlrev_b32_e32 v148, 16, v167
	v_mul_f32_e32 v84, v149, v149
	v_and_b32_e32 v151, 0xffff0000, v166
	v_pk_fma_f32 v[224:225], v[148:149], v[148:149], v[84:85] op_sel_hi:[1,1,0]
	v_lshlrev_b32_e32 v150, 16, v166
	v_mul_f32_e32 v84, v151, v151
	v_and_b32_e32 v153, 0xffff0000, v165
	v_pk_fma_f32 v[226:227], v[150:151], v[150:151], v[84:85] op_sel_hi:[1,1,0]
	v_lshlrev_b32_e32 v152, 16, v165
	v_mul_f32_e32 v84, v153, v153
	v_and_b32_e32 v159, 0xffff0000, v164
	v_pk_fma_f32 v[228:229], v[152:153], v[152:153], v[84:85] op_sel_hi:[1,1,0]
	v_lshlrev_b32_e32 v158, 16, v164
	v_mul_f32_e32 v84, v159, v159
	v_and_b32_e32 v165, 0xffff0000, v175
	v_pk_fma_f32 v[230:231], v[158:159], v[158:159], v[84:85] op_sel_hi:[1,1,0]
	v_lshlrev_b32_e32 v164, 16, v175
	v_mul_f32_e32 v84, v165, v165
	v_and_b32_e32 v167, 0xffff0000, v174
	v_pk_fma_f32 v[232:233], v[164:165], v[164:165], v[84:85] op_sel_hi:[1,1,0]
	v_lshlrev_b32_e32 v166, 16, v174
	v_mul_f32_e32 v84, v167, v167
	v_and_b32_e32 v169, 0xffff0000, v173
	v_pk_fma_f32 v[234:235], v[166:167], v[166:167], v[84:85] op_sel_hi:[1,1,0]
	v_lshlrev_b32_e32 v168, 16, v173
	v_mul_f32_e32 v84, v169, v169
	v_and_b32_e32 v171, 0xffff0000, v172
	v_and_b32_e32 v175, 0xffff0000, v82
	v_pk_fma_f32 v[236:237], v[168:169], v[168:169], v[84:85] op_sel_hi:[1,1,0]
	v_lshlrev_b32_e32 v170, 16, v172
	v_mul_f32_e32 v84, v171, v171
	v_and_b32_e32 v173, 0xffff0000, v83
	v_lshlrev_b32_e32 v174, 16, v82
	v_mul_f32_e32 v82, v175, v175
	v_pk_fma_f32 v[238:239], v[170:171], v[170:171], v[84:85] op_sel_hi:[1,1,0]
	v_lshlrev_b32_e32 v172, 16, v83
	v_mul_f32_e32 v84, v173, v173
	v_pk_fma_f32 v[242:243], v[174:175], v[174:175], v[82:83] op_sel_hi:[1,1,0]
	v_and_b32_e32 v83, 0xffff0000, v81
	v_pk_fma_f32 v[240:241], v[172:173], v[172:173], v[84:85] op_sel_hi:[1,1,0]
	v_lshlrev_b32_e32 v82, 16, v81
	v_mul_f32_e32 v84, v83, v83
	v_lshlrev_b32_e32 v176, 16, v80
	v_mul_f32_e32 v80, v177, v177
	v_pk_fma_f32 v[244:245], v[82:83], v[82:83], v[84:85] op_sel_hi:[1,1,0]
	v_pk_fma_f32 v[80:81], v[176:177], v[176:177], v[80:81] op_sel_hi:[1,1,0]
	s_nop 0
	v_pk_add_f32 v[80:81], v[80:81], v[244:245]
	s_nop 0
	v_pk_add_f32 v[80:81], v[242:243], v[80:81]
	s_nop 0
	v_pk_add_f32 v[80:81], v[240:241], v[80:81]
	s_nop 0
	v_pk_add_f32 v[80:81], v[238:239], v[80:81]
	s_nop 0
	v_pk_add_f32 v[80:81], v[236:237], v[80:81]
	s_nop 0
	v_pk_add_f32 v[80:81], v[234:235], v[80:81]
	s_nop 0
	v_pk_add_f32 v[80:81], v[232:233], v[80:81]
	s_nop 0
	v_pk_add_f32 v[80:81], v[230:231], v[80:81]
	s_nop 0
	v_pk_add_f32 v[80:81], v[228:229], v[80:81]
	s_nop 0
	v_pk_add_f32 v[80:81], v[226:227], v[80:81]
	s_nop 0
	v_pk_add_f32 v[80:81], v[224:225], v[80:81]
	s_nop 0
	v_pk_add_f32 v[80:81], v[222:223], v[80:81]
	s_nop 0
	v_pk_add_f32 v[80:81], v[220:221], v[80:81]
	s_nop 0
	v_pk_add_f32 v[80:81], v[218:219], v[80:81]
	s_nop 0
	v_pk_add_f32 v[80:81], v[216:217], v[80:81]
	s_nop 0
	v_pk_add_f32 v[80:81], v[214:215], v[80:81]
	s_nop 0
	v_pk_add_f32 v[80:81], v[212:213], v[80:81]
	s_nop 0
	v_pk_add_f32 v[80:81], v[210:211], v[80:81]
	s_nop 0
	v_pk_add_f32 v[80:81], v[208:209], v[80:81]
	s_nop 0
	v_pk_add_f32 v[80:81], v[206:207], v[80:81]
	s_nop 0
	v_pk_add_f32 v[80:81], v[204:205], v[80:81]
	s_nop 0
	v_pk_add_f32 v[80:81], v[202:203], v[80:81]
	s_nop 0
	v_pk_add_f32 v[80:81], v[200:201], v[80:81]
	s_nop 0
	v_pk_add_f32 v[80:81], v[198:199], v[80:81]
	s_nop 0
	v_pk_add_f32 v[80:81], v[196:197], v[80:81]
	s_nop 0
	v_pk_add_f32 v[80:81], v[194:195], v[80:81] op_sel:[1,0] op_sel_hi:[0,1]
	v_pk_add_f32 v[80:81], v[194:195], v[80:81]
	s_nop 0
	v_pk_add_f32 v[80:81], v[192:193], v[80:81] op_sel:[1,0] op_sel_hi:[0,1]
	v_pk_add_f32 v[80:81], v[192:193], v[80:81]
	s_nop 0
	v_pk_add_f32 v[80:81], v[190:191], v[80:81] op_sel:[1,0] op_sel_hi:[0,1]
	v_pk_add_f32 v[80:81], v[190:191], v[80:81]
	s_nop 0
	v_mov_b32_e32 v81, v80
	s_nop 1
	v_permlane32_swap_b32_e32 v80, v81
	s_and_saveexec_b64 s[56:57], s[0:1]
	v_add_u32_e32 v84, 0, v187
	ds_write_b128 v84, v[112:115] offset:34816
	s_or_b64 exec, exec, s[56:57]
	v_add_f32_e32 v80, v80, v81
	v_fmamk_f32 v80, v80, 0x3c000000, v178
	v_mul_f32_e32 v81, 0x4b800000, v80
	v_cmp_gt_f32_e32 vcc, s68, v80
	v_mov_b32_e32 v123, v85
	v_mov_b32_e32 v109, v87
	v_cndmask_b32_e32 v80, v80, v81, vcc
	v_rsq_f32_e32 v80, v80
	v_mov_b32_e32 v111, v89
	v_mov_b32_e32 v127, v91
	v_mov_b32_e32 v125, v93
	v_mul_f32_e32 v81, 0x45800000, v80
	v_cndmask_b32_e32 v188, v80, v81, vcc
	v_pk_mul_f32 v[80:81], v[188:189], v[176:177] op_sel_hi:[0,1]
	s_waitcnt lgkmcnt(14)
	v_pk_mul_f32 v[76:77], v[76:77], v[80:81]
	v_mov_b32_e32 v107, v95
	v_cvt_pk_bf16_f32 v80, v76, v77
	v_pk_mul_f32 v[76:77], v[188:189], v[82:83] op_sel_hi:[0,1]
	v_pk_mul_f32 v[76:77], v[78:79], v[76:77]
	s_add_i32 s82, s3, s59
	v_cvt_pk_bf16_f32 v81, v76, v77
	v_pk_mul_f32 v[76:77], v[188:189], v[174:175] op_sel_hi:[0,1]
	v_pk_mul_f32 v[72:73], v[72:73], v[76:77]
	v_mul_lo_u32 v174, v119, s69
	v_cvt_pk_bf16_f32 v82, v72, v73
	v_pk_mul_f32 v[72:73], v[188:189], v[172:173] op_sel_hi:[0,1]
	v_pk_mul_f32 v[72:73], v[74:75], v[72:73]
	v_mul_lo_u32 v175, v189, s69
	v_cvt_pk_bf16_f32 v83, v72, v73
	v_pk_mul_f32 v[72:73], v[188:189], v[170:171] op_sel_hi:[0,1]
	s_waitcnt lgkmcnt(13)
	v_pk_mul_f32 v[68:69], v[68:69], v[72:73]
	s_add_i32 s15, s82, 16
	v_cvt_pk_bf16_f32 v84, v68, v69
	v_pk_mul_f32 v[68:69], v[188:189], v[168:169] op_sel_hi:[0,1]
	v_pk_mul_f32 v[68:69], v[70:71], v[68:69]
	v_lshlrev_b32_e32 v163, 3, v121
	v_cvt_pk_bf16_f32 v85, v68, v69
	v_pk_mul_f32 v[68:69], v[188:189], v[166:167] op_sel_hi:[0,1]
	s_waitcnt lgkmcnt(12)
	v_pk_mul_f32 v[64:65], v[64:65], v[68:69]
	s_add_i32 s82, s82, 47
	v_cvt_pk_bf16_f32 v86, v64, v65
	v_pk_mul_f32 v[64:65], v[188:189], v[164:165] op_sel_hi:[0,1]
	v_pk_mul_f32 v[64:65], v[66:67], v[64:65]
	s_mov_b32 s64, 1
	v_cvt_pk_bf16_f32 v87, v64, v65
	v_pk_mul_f32 v[64:65], v[188:189], v[158:159] op_sel_hi:[0,1]
	s_waitcnt lgkmcnt(11)
	v_pk_mul_f32 v[60:61], v[60:61], v[64:65]
	v_lshlrev_b32_e32 v159, 2, v121
	v_cvt_pk_bf16_f32 v88, v60, v61
	v_pk_mul_f32 v[60:61], v[188:189], v[152:153] op_sel_hi:[0,1]
	v_pk_mul_f32 v[60:61], v[62:63], v[60:61]
	v_add_u32_e32 v158, s15, v186
	v_cvt_pk_bf16_f32 v89, v60, v61
	v_pk_mul_f32 v[60:61], v[188:189], v[150:151] op_sel_hi:[0,1]
	s_waitcnt lgkmcnt(10)
	v_pk_mul_f32 v[56:57], v[56:57], v[60:61]
	v_mov_b32_e32 v60, v129
	v_cvt_pk_bf16_f32 v90, v56, v57
	v_pk_mul_f32 v[56:57], v[188:189], v[148:149] op_sel_hi:[0,1]
	v_pk_mul_f32 v[56:57], v[58:59], v[56:57]
	v_mov_b32_e32 v58, v129
	v_cvt_pk_bf16_f32 v91, v56, v57
	v_pk_mul_f32 v[56:57], v[188:189], v[146:147] op_sel_hi:[0,1]
	s_waitcnt lgkmcnt(9)
	v_pk_mul_f32 v[52:53], v[52:53], v[56:57]
	v_mov_b32_e32 v56, v129
	v_cvt_pk_bf16_f32 v92, v52, v53
	v_pk_mul_f32 v[52:53], v[188:189], v[144:145] op_sel_hi:[0,1]
	v_pk_mul_f32 v[52:53], v[54:55], v[52:53]
	v_mov_b32_e32 v54, v129
	v_cvt_pk_bf16_f32 v93, v52, v53
	v_pk_mul_f32 v[52:53], v[188:189], v[142:143] op_sel_hi:[0,1]
	s_waitcnt lgkmcnt(8)
	v_pk_mul_f32 v[48:49], v[48:49], v[52:53]
	v_mov_b32_e32 v52, v129
	v_cvt_pk_bf16_f32 v94, v48, v49
	v_pk_mul_f32 v[48:49], v[188:189], v[140:141] op_sel_hi:[0,1]
	v_pk_mul_f32 v[48:49], v[50:51], v[48:49]
	v_mov_b32_e32 v50, v129
	v_cvt_pk_bf16_f32 v95, v48, v49
	v_pk_mul_f32 v[48:49], v[188:189], v[96:97] op_sel_hi:[0,1]
	s_waitcnt lgkmcnt(7)
	v_pk_mul_f32 v[44:45], v[44:45], v[48:49]
	v_mov_b32_e32 v48, v129
	v_cvt_pk_bf16_f32 v96, v44, v45
	v_pk_mul_f32 v[44:45], v[188:189], v[138:139] op_sel_hi:[0,1]
	v_pk_mul_f32 v[44:45], v[46:47], v[44:45]
	v_mov_b32_e32 v49, v129
	v_cvt_pk_bf16_f32 v97, v44, v45
	v_pk_mul_f32 v[44:45], v[188:189], v[98:99] op_sel_hi:[0,1]
	s_waitcnt lgkmcnt(6)
	v_pk_mul_f32 v[40:41], v[40:41], v[44:45]
	v_mov_b32_e32 v51, v129
	v_cvt_pk_bf16_f32 v98, v40, v41
	v_pk_mul_f32 v[40:41], v[188:189], v[136:137] op_sel_hi:[0,1]
	v_pk_mul_f32 v[40:41], v[42:43], v[40:41]
	v_mov_b32_e32 v53, v129
	v_cvt_pk_bf16_f32 v99, v40, v41
	v_pk_mul_f32 v[40:41], v[188:189], v[100:101] op_sel_hi:[0,1]
	s_waitcnt lgkmcnt(5)
	v_pk_mul_f32 v[36:37], v[40:41], v[36:37]
	v_mov_b32_e32 v55, v129
	v_cvt_pk_bf16_f32 v100, v36, v37
	v_pk_mul_f32 v[36:37], v[188:189], v[134:135] op_sel_hi:[0,1]
	v_pk_mul_f32 v[36:37], v[36:37], v[38:39]
	v_mov_b32_e32 v57, v129
	v_cvt_pk_bf16_f32 v101, v36, v37
	v_pk_mul_f32 v[36:37], v[188:189], v[102:103] op_sel_hi:[0,1]
	s_waitcnt lgkmcnt(4)
	v_pk_mul_f32 v[32:33], v[36:37], v[32:33]
	v_mov_b32_e32 v59, v129
	v_cvt_pk_bf16_f32 v102, v32, v33
	v_pk_mul_f32 v[32:33], v[188:189], v[132:133] op_sel_hi:[0,1]
	v_pk_mul_f32 v[32:33], v[32:33], v[34:35]
	v_mov_b32_e32 v61, v129
	v_cvt_pk_bf16_f32 v103, v32, v33
	v_pk_mul_f32 v[32:33], v[188:189], v[104:105] op_sel_hi:[0,1]
	s_waitcnt lgkmcnt(3)
	v_pk_mul_f32 v[28:29], v[32:33], v[28:29]
	v_mov_b32_e32 v62, v129
	v_cvt_pk_bf16_f32 v104, v28, v29
	v_pk_mul_f32 v[28:29], v[188:189], v[130:131] op_sel_hi:[0,1]
	v_pk_mul_f32 v[28:29], v[28:29], v[30:31]
	v_mov_b32_e32 v63, v129
	v_cvt_pk_bf16_f32 v105, v28, v29
	v_pk_mul_f32 v[28:29], v[188:189], v[106:107] op_sel_hi:[0,1]
	s_waitcnt lgkmcnt(2)
	v_pk_mul_f32 v[24:25], v[28:29], v[24:25]
	v_mov_b64_e32 v[32:33], v[48:49]
	v_cvt_pk_bf16_f32 v106, v24, v25
	v_pk_mul_f32 v[24:25], v[188:189], v[126:127] op_sel_hi:[0,1]
	v_pk_mul_f32 v[24:25], v[24:25], v[26:27]
	v_mul_u32_u24_e32 v169, 0x110, v186
	v_cvt_pk_bf16_f32 v107, v24, v25
	v_pk_mul_f32 v[24:25], v[188:189], v[108:109] op_sel_hi:[0,1]
	s_waitcnt lgkmcnt(1)
	v_pk_mul_f32 v[20:21], v[24:25], v[20:21]
	v_mov_b32_e32 v155, v158
	v_cvt_pk_bf16_f32 v108, v20, v21
	v_pk_mul_f32 v[20:21], v[188:189], v[124:125] op_sel_hi:[0,1]
	v_pk_mul_f32 v[20:21], v[20:21], v[22:23]
	v_lshl_add_u64 v[164:165], v[116:117], 2, s[4:5]
	v_cvt_pk_bf16_f32 v109, v20, v21
	v_pk_mul_f32 v[20:21], v[188:189], v[110:111] op_sel_hi:[0,1]
	s_waitcnt lgkmcnt(0)
	v_pk_mul_f32 v[16:17], v[20:21], v[16:17]
	v_add_u32_e32 v20, 0, v128
	v_cvt_pk_bf16_f32 v110, v16, v17
	v_pk_mul_f32 v[16:17], v[188:189], v[122:123] op_sel_hi:[0,1]
	v_pk_mul_f32 v[16:17], v[16:17], v[18:19]
	v_and_b32_e32 v19, 16, v154
	v_cvt_pk_bf16_f32 v111, v16, v17
	v_lshlrev_b32_e32 v16, 16, v12
	v_and_b32_e32 v17, 0xffff0000, v12
	v_pk_mul_f32 v[16:17], v[120:121], v[16:17] op_sel_hi:[0,1]
	v_cvt_pk_bf16_f32 v12, v16, v17
	v_lshlrev_b32_e32 v16, 16, v13
	v_and_b32_e32 v17, 0xffff0000, v13
	v_pk_mul_f32 v[16:17], v[120:121], v[16:17] op_sel_hi:[0,1]
	v_cvt_pk_bf16_f32 v13, v16, v17
	v_lshlrev_b32_e32 v16, 16, v14
	v_and_b32_e32 v17, 0xffff0000, v14
	v_pk_mul_f32 v[16:17], v[120:121], v[16:17] op_sel_hi:[0,1]
	v_cvt_pk_bf16_f32 v14, v16, v17
	v_lshlrev_b32_e32 v16, 16, v15
	v_and_b32_e32 v17, 0xffff0000, v15
	v_pk_mul_f32 v[16:17], v[120:121], v[16:17] op_sel_hi:[0,1]
	v_cvt_pk_bf16_f32 v15, v16, v17
	v_add_u32_e32 v16, v20, v174
	ds_write_b128 v16, v[12:15]
	ds_write_b128 v248, v[8:11] offset:17408
	v_lshlrev_b32_e32 v8, 16, v4
	v_and_b32_e32 v9, 0xffff0000, v4
	v_pk_mul_f32 v[8:9], v[118:119], v[8:9] op_sel_hi:[0,1]
	v_cvt_pk_bf16_f32 v4, v8, v9
	v_lshlrev_b32_e32 v8, 16, v5
	v_and_b32_e32 v9, 0xffff0000, v5
	v_pk_mul_f32 v[8:9], v[118:119], v[8:9] op_sel_hi:[0,1]
	v_cvt_pk_bf16_f32 v5, v8, v9
	v_lshlrev_b32_e32 v8, 16, v6
	v_and_b32_e32 v9, 0xffff0000, v6
	v_pk_mul_f32 v[8:9], v[118:119], v[8:9] op_sel_hi:[0,1]
	v_cvt_pk_bf16_f32 v6, v8, v9
	v_lshlrev_b32_e32 v8, 16, v7
	v_and_b32_e32 v9, 0xffff0000, v7
	v_pk_mul_f32 v[8:9], v[118:119], v[8:9] op_sel_hi:[0,1]
	v_cvt_pk_bf16_f32 v7, v8, v9
	v_add_u32_e32 v8, v20, v175
	ds_write_b128 v8, v[4:7]
	ds_write_b128 v248, v[0:3] offset:25600
	v_lshlrev_b32_e32 v1, 2, v185
	v_lshrrev_b32_e32 v18, 2, v154
	v_and_or_b32 v1, v1, 12, v19
	v_and_or_b32 v0, v18, 3, v159
	v_lshlrev_b32_e32 v177, 1, v1
	v_or_b32_e32 v1, 32, v185
	v_mul_u32_u24_e32 v176, 0x110, v1
	v_mul_u32_u24_e32 v188, 0x110, v0
	v_mov_b64_e32 v[16:17], v[48:49]
	v_mov_b64_e32 v[0:1], v[48:49]
	s_and_b32 s12, s58, 0xfc0
	v_subrev_u32_e32 v189, 64, v189
	v_subrev_u32_e32 v190, 64, v119
	v_mov_b32_e32 v167, 0
	v_mov_b32_e32 v192, 0xff800000
	v_mov_b64_e32 v[34:35], v[50:51]
	v_mov_b64_e32 v[36:37], v[52:53]
	v_mov_b64_e32 v[38:39], v[54:55]
	v_mov_b64_e32 v[40:41], v[56:57]
	v_mov_b64_e32 v[42:43], v[58:59]
	v_mov_b64_e32 v[44:45], v[60:61]
	v_mov_b64_e32 v[46:47], v[62:63]
	v_mov_b64_e32 v[18:19], v[50:51]
	v_mov_b64_e32 v[20:21], v[52:53]
	v_mov_b64_e32 v[22:23], v[54:55]
	v_mov_b64_e32 v[24:25], v[56:57]
	v_mov_b64_e32 v[26:27], v[58:59]
	v_mov_b64_e32 v[28:29], v[60:61]
	v_mov_b64_e32 v[30:31], v[62:63]
	v_mov_b64_e32 v[2:3], v[50:51]
	v_mov_b64_e32 v[4:5], v[52:53]
	v_mov_b64_e32 v[6:7], v[54:55]
	v_mov_b64_e32 v[8:9], v[56:57]
	v_mov_b64_e32 v[10:11], v[58:59]
	v_mov_b64_e32 v[12:13], v[60:61]
	v_mov_b64_e32 v[14:15], v[62:63]
	s_waitcnt lgkmcnt(0)
	s_barrier
	s_branch .LBB0_507
.LBB0_506:
	s_or_b64 exec, exec, s[4:5]
	s_waitcnt vmcnt(5)
	v_lshlrev_b32_e32 v64, 16, v130
	v_and_b32_e32 v65, 0xffff0000, v130
	v_lshlrev_b32_e32 v66, 16, v131
	v_and_b32_e32 v67, 0xffff0000, v131
	s_waitcnt vmcnt(3)
	v_pk_mul_f32 v[64:65], v[168:169], v[64:65] op_sel_hi:[0,1]
	v_pk_mul_f32 v[66:67], v[168:169], v[66:67] op_sel_hi:[0,1]
	v_cvt_pk_bf16_f32 v64, v64, v65
	v_cvt_pk_bf16_f32 v65, v66, v67
	v_lshlrev_b32_e32 v66, 16, v132
	v_and_b32_e32 v67, 0xffff0000, v132
	v_lshlrev_b32_e32 v68, 16, v133
	v_and_b32_e32 v69, 0xffff0000, v133
	v_add_u32_e32 v70, s56, v128
	v_pk_mul_f32 v[66:67], v[168:169], v[66:67] op_sel_hi:[0,1]
	v_pk_mul_f32 v[68:69], v[168:169], v[68:69] op_sel_hi:[0,1]
	v_cvt_pk_bf16_f32 v66, v66, v67
	v_cvt_pk_bf16_f32 v67, v68, v69
	v_add_u32_e32 v68, v70, v174
	ds_write_b128 v68, v[64:67]
	v_add_u32_e32 v71, s56, v248
	ds_write_b128 v71, v[116:119] offset:17408
	s_waitcnt vmcnt(2)
	v_lshlrev_b32_e32 v64, 16, v120
	v_and_b32_e32 v65, 0xffff0000, v120
	v_lshlrev_b32_e32 v66, 16, v121
	v_and_b32_e32 v67, 0xffff0000, v121
	s_waitcnt vmcnt(0)
	v_pk_mul_f32 v[64:65], v[166:167], v[64:65] op_sel_hi:[0,1]
	v_pk_mul_f32 v[66:67], v[166:167], v[66:67] op_sel_hi:[0,1]
	v_cvt_pk_bf16_f32 v64, v64, v65
	v_cvt_pk_bf16_f32 v65, v66, v67
	v_lshlrev_b32_e32 v66, 16, v122
	v_and_b32_e32 v67, 0xffff0000, v122
	v_lshlrev_b32_e32 v68, 16, v123
	v_and_b32_e32 v69, 0xffff0000, v123
	v_pk_mul_f32 v[66:67], v[166:167], v[66:67] op_sel_hi:[0,1]
	v_pk_mul_f32 v[68:69], v[166:167], v[68:69] op_sel_hi:[0,1]
	s_sub_i32 s12, s12, 64
	s_add_i32 s64, s64, 1
	v_cvt_pk_bf16_f32 v66, v66, v67
	v_cvt_pk_bf16_f32 v67, v68, v69
	v_add_u32_e32 v68, v70, v175
	s_cmp_eq_u32 s12, 0
	ds_write_b128 v68, v[64:67]
	ds_write_b128 v71, v[124:127] offset:25600
	s_waitcnt lgkmcnt(0)
	s_barrier
	s_cbranch_scc1 .LBB0_568

.LBB0_509:
	s_or_b64 exec, exec, s[4:5]
	v_add_u32_e32 v65, s12, v190
	v_mov_b32_e32 v70, s33
	v_cmp_lt_i32_e32 vcc, 15, v65
	v_min_i32_e32 v64, 0x80f, v65
	s_and_b32 s89, 1, s64
	v_cndmask_b32_e32 v65, v179, v70, vcc
	v_add_u32_e32 v66, v65, v64
	v_ashrrev_i32_e32 v67, 31, v66
	v_lshlrev_b64 v[66:67], 14, v[66:67]
	v_lshl_add_u64 v[66:67], v[160:161], 0, v[66:67]
	v_add_co_u32_e32 v68, vcc, s65, v66
	v_ashrrev_i32_e32 v65, 31, v64
	s_nop 0
	v_addc_co_u32_e32 v69, vcc, 0, v67, vcc
	v_add_co_u32_e32 v66, vcc, s63, v66
	v_lshl_add_u64 v[64:65], v[64:65], 2, s[54:55]
	s_nop 0
	v_addc_co_u32_e32 v67, vcc, 0, v67, vcc
	global_load_dwordx4 v[130:133], v[68:69], off offset:2048
	global_load_dwordx4 v[116:119], v[66:67], off
	v_add_u32_e32 v67, s12, v189
	v_cmp_lt_i32_e32 vcc, 15, v67
	v_min_i32_e32 v66, 0x80f, v67
	s_cselect_b32 s4, 0, 0x8a00
	v_cndmask_b32_e32 v67, v179, v70, vcc
	v_add_u32_e32 v68, v67, v66
	v_ashrrev_i32_e32 v69, 31, v68
	v_lshlrev_b64 v[68:69], 14, v[68:69]
	v_lshl_add_u64 v[68:69], v[160:161], 0, v[68:69]
	v_add_co_u32_e32 v70, vcc, 0x2000, v68
	v_ashrrev_i32_e32 v67, 31, v66
	s_nop 0
	v_addc_co_u32_e32 v71, vcc, 0, v69, vcc
	global_load_dword v168, v[64:65], off
	global_load_dwordx4 v[120:123], v[70:71], off offset:2048
	v_add_co_u32_e32 v64, vcc, 0x3000, v68
	v_lshl_add_u64 v[66:67], v[66:67], 2, s[54:55]
	s_nop 0
	v_addc_co_u32_e32 v65, vcc, 0, v69, vcc
	global_load_dwordx4 v[124:127], v[64:65], off
	global_load_dword v166, v[66:67], off
	s_add_i32 s4, s4, 0
	v_add_u32_e32 v193, s4, v162
	v_add_u32_e32 v64, s4, v177
	v_add_u32_e32 v191, s4, v247
	s_add_i32 s4, s12, 32
	s_cmp_gt_i32 s4, s82
	s_cbranch_scc1 .LBB0_530
	v_add_u32_e32 v68, v193, v176
	ds_read_b128 v[64:67], v68
	ds_read_b128 v[134:137], v68 offset:32
	ds_read_b128 v[138:141], v68 offset:64
	ds_read_b128 v[142:145], v68 offset:96
	ds_read_b128 v[150:153], v68 offset:128
	ds_read_b128 v[170:173], v68 offset:160
	ds_read_b128 v[194:197], v68 offset:192
	ds_read_b128 v[198:201], v68 offset:224
	s_waitcnt lgkmcnt(7)
	v_mfma_f32_32x32x16_bf16 v[64:79], v[64:67], v[80:83], 0
	s_add_i32 s4, s12, 63
	s_cmp_le_i32 s4, s15
	s_cselect_b64 s[56:57], -1, 0
	s_cmp_gt_i32 s4, s15
	s_mov_b64 s[4:5], -1
	s_waitcnt lgkmcnt(6)
	v_mfma_f32_32x32x16_bf16 v[64:79], v[134:137], v[84:87], v[64:79]
	s_waitcnt lgkmcnt(5)
	v_mfma_f32_32x32x16_bf16 v[64:79], v[138:141], v[88:91], v[64:79]
	s_waitcnt lgkmcnt(4)
	v_mfma_f32_32x32x16_bf16 v[64:79], v[142:145], v[92:95], v[64:79]
	ds_read_b64_tr_b16 v[146:147], v191 offset:25600
	ds_read_b64_tr_b16 v[148:149], v191 offset:27648
	ds_read_b64_tr_b16 v[142:143], v191 offset:29696
	ds_read_b64_tr_b16 v[144:145], v191 offset:31744
	ds_read_b64_tr_b16 v[138:139], v191 offset:26112
	ds_read_b64_tr_b16 v[140:141], v191 offset:28160
	ds_read_b64_tr_b16 v[134:135], v191 offset:30208
	ds_read_b64_tr_b16 v[136:137], v191 offset:32256
	s_waitcnt lgkmcnt(11)
	v_mfma_f32_32x32x16_bf16 v[64:79], v[150:153], v[96:99], v[64:79]
	ds_read_b128 v[150:153], v193 offset:34944
	s_waitcnt lgkmcnt(11)
	v_mfma_f32_32x32x16_bf16 v[64:79], v[170:173], v[100:103], v[64:79]
	s_waitcnt lgkmcnt(0)
	v_xor_b32_e32 v173, 0x80000000, v152
	v_mfma_f32_32x32x16_bf16 v[64:79], v[194:197], v[104:107], v[64:79]
	v_mfma_f32_32x32x16_bf16 v[64:79], v[198:201], v[108:111], v[64:79]
	s_nop 11
	v_sub_f32_e32 v195, v64, v150
	s_cbranch_scc1 .LBB0_512
	v_mov_b32_e32 v170, v65
	v_mov_b32_e32 v171, v66
	v_xor_b32_e32 v172, 0x80000000, v151
	v_pk_add_f32 v[170:171], v[170:171], v[172:173]
	v_sub_f32_e32 v172, v67, v153
	v_max3_f32 v64, v195, s87, v170
	v_max3_f32 v196, v64, v171, v172
	s_mov_b64 s[4:5], 0

.LBB0_528:
	v_sub_f32_e32 v65, v195, v64
	v_exp_f32_e32 v173, v65
	v_sub_f32_e32 v65, v170, v64
	v_exp_f32_e32 v170, v65
	v_sub_f32_e32 v65, v171, v64
	v_exp_f32_e32 v171, v65
	v_sub_f32_e32 v65, v172, v64
	v_exp_f32_e32 v172, v65
	v_sub_f32_e32 v65, v150, v64
	v_exp_f32_e32 v150, v65
	v_sub_f32_e32 v65, v151, v64
	v_exp_f32_e32 v151, v65
	v_sub_f32_e32 v65, v152, v64
	v_exp_f32_e32 v152, v65
	v_sub_f32_e32 v65, v153, v64
	v_exp_f32_e32 v153, v65
	v_sub_f32_e32 v65, v68, v64
	v_exp_f32_e32 v192, v65
	v_sub_f32_e32 v65, v69, v64
	v_exp_f32_e32 v195, v65
	v_sub_f32_e32 v65, v70, v64
	v_exp_f32_e32 v196, v65
	v_sub_f32_e32 v65, v71, v64
	v_cvt_pk_bf16_f32 v68, v173, v170
	v_cvt_pk_bf16_f32 v69, v171, v172
	v_cvt_pk_bf16_f32 v70, v150, v151
	v_cvt_pk_bf16_f32 v71, v152, v153
	v_exp_f32_e32 v197, v65
	v_sub_f32_e32 v65, v72, v64
	v_mfma_f32_32x32x16_bf16 v[32:47], v[138:141], v[68:71], v[32:47]
	v_exp_f32_e32 v198, v65
	v_sub_f32_e32 v65, v73, v64
	v_exp_f32_e32 v199, v65
	v_sub_f32_e32 v65, v66, v64
	v_sub_f32_e32 v64, v67, v64
	ds_read_b64_tr_b16 v[72:73], v191 offset:26624
	v_cvt_pk_bf16_f32 v66, v198, v199
	v_mfma_f32_32x32x16_bf16 v[48:63], v[146:149], v[68:71], v[48:63]
	v_exp_f32_e32 v146, v65
	v_exp_f32_e32 v147, v64
	v_cvt_pk_bf16_f32 v64, v192, v195
	v_cvt_pk_bf16_f32 v65, v196, v197
	v_cvt_pk_bf16_f32 v67, v146, v147
	s_nop 1
	v_mfma_f32_32x32x16_bf16 v[32:47], v[134:137], v[64:67], v[32:47]
	ds_read_b64_tr_b16 v[74:75], v191 offset:28672
	ds_read_b64_tr_b16 v[76:77], v191 offset:30720
	ds_read_b64_tr_b16 v[134:135], v191 offset:31232
	ds_read_b64_tr_b16 v[140:141], v191 offset:29184
	ds_read_b64_tr_b16 v[138:139], v191 offset:27136
	ds_read_b64_tr_b16 v[136:137], v191 offset:33280
	ds_read_b64_tr_b16 v[78:79], v191 offset:32768
	s_waitcnt lgkmcnt(6)
	v_mfma_f32_32x32x16_bf16 v[16:31], v[72:75], v[68:71], v[16:31]
	v_add_f32_e32 v72, 0, v173
	v_add_f32_e32 v72, v170, v72
	v_add_f32_e32 v72, v171, v72
	v_add_f32_e32 v72, v172, v72
	v_add_f32_e32 v72, v150, v72
	v_add_f32_e32 v72, v151, v72
	v_add_f32_e32 v72, v152, v72
	s_waitcnt lgkmcnt(2)
	v_mfma_f32_32x32x16_bf16 v[0:15], v[138:141], v[68:71], v[0:15]
	v_add_f32_e32 v72, v153, v72
	v_add_f32_e32 v72, v192, v72
	v_add_f32_e32 v72, v195, v72
	v_add_f32_e32 v68, v196, v72
	v_add_f32_e32 v68, v197, v68
	v_add_f32_e32 v68, v198, v68
	v_add_f32_e32 v68, v199, v68
	v_mfma_f32_32x32x16_bf16 v[48:63], v[142:145], v[64:67], v[48:63]
	v_add_f32_e32 v68, v146, v68
	v_add_f32_e32 v68, v147, v68
	v_add_f32_e32 v167, v68, v167
	s_waitcnt lgkmcnt(0)
	v_mfma_f32_32x32x16_bf16 v[16:31], v[76:79], v[64:67], v[16:31]
	v_mfma_f32_32x32x16_bf16 v[0:15], v[134:137], v[64:67], v[0:15]
	s_cmp_gt_i32 s12, s82
	s_cbranch_scc0 .LBB0_531

.LBB0_531:
	v_add_u32_e32 v68, v193, v169
	ds_read_b128 v[64:67], v68
	ds_read_b128 v[134:137], v68 offset:32
	ds_read_b128 v[138:141], v68 offset:64
	ds_read_b128 v[142:145], v68 offset:96
	ds_read_b128 v[150:153], v68 offset:128
	ds_read_b128 v[170:173], v68 offset:160
	ds_read_b128 v[196:199], v68 offset:192
	ds_read_b128 v[200:203], v68 offset:224
	s_waitcnt lgkmcnt(7)
	v_mfma_f32_32x32x16_bf16 v[64:79], v[64:67], v[80:83], 0
	s_add_i32 s4, s12, 31
	s_cmp_le_i32 s4, s15
	s_cselect_b64 s[56:57], -1, 0
	s_cmp_gt_i32 s4, s15
	s_mov_b64 s[4:5], -1
	s_waitcnt lgkmcnt(6)
	v_mfma_f32_32x32x16_bf16 v[64:79], v[134:137], v[84:87], v[64:79]
	s_waitcnt lgkmcnt(5)
	v_mfma_f32_32x32x16_bf16 v[64:79], v[138:141], v[88:91], v[64:79]
	s_waitcnt lgkmcnt(4)
	v_mfma_f32_32x32x16_bf16 v[64:79], v[142:145], v[92:95], v[64:79]
	ds_read_b64_tr_b16 v[146:147], v191 offset:17408
	ds_read_b64_tr_b16 v[148:149], v191 offset:19456
	ds_read_b64_tr_b16 v[142:143], v191 offset:21504
	ds_read_b64_tr_b16 v[144:145], v191 offset:23552
	ds_read_b64_tr_b16 v[138:139], v191 offset:17920
	ds_read_b64_tr_b16 v[140:141], v191 offset:19968
	ds_read_b64_tr_b16 v[134:135], v191 offset:22016
	ds_read_b64_tr_b16 v[136:137], v191 offset:24064
	s_waitcnt lgkmcnt(11)
	v_mfma_f32_32x32x16_bf16 v[64:79], v[150:153], v[96:99], v[64:79]
	ds_read_b128 v[150:153], v193 offset:34816
	s_waitcnt lgkmcnt(11)
	v_mfma_f32_32x32x16_bf16 v[64:79], v[170:173], v[100:103], v[64:79]
	s_waitcnt lgkmcnt(0)
	v_xor_b32_e32 v173, 0x80000000, v152
	v_mfma_f32_32x32x16_bf16 v[64:79], v[196:199], v[104:107], v[64:79]
	v_mfma_f32_32x32x16_bf16 v[64:79], v[200:203], v[108:111], v[64:79]
	s_nop 11
	v_sub_f32_e32 v195, v64, v150
	s_cbranch_scc1 .LBB0_533
	v_mov_b32_e32 v170, v65
	v_mov_b32_e32 v171, v66
	v_xor_b32_e32 v172, 0x80000000, v151
	v_pk_add_f32 v[170:171], v[170:171], v[172:173]
	v_sub_f32_e32 v172, v67, v153
	v_max3_f32 v64, v195, s87, v170
	v_max3_f32 v196, v64, v171, v172
	s_mov_b64 s[4:5], 0

.LBB0_549:
	v_sub_f32_e32 v65, v195, v64
	v_exp_f32_e32 v173, v65
	v_sub_f32_e32 v65, v170, v64
	v_exp_f32_e32 v170, v65
	v_sub_f32_e32 v65, v171, v64
	v_exp_f32_e32 v171, v65
	v_sub_f32_e32 v65, v172, v64
	v_exp_f32_e32 v172, v65
	v_sub_f32_e32 v65, v150, v64
	v_exp_f32_e32 v150, v65
	v_sub_f32_e32 v65, v151, v64
	v_exp_f32_e32 v151, v65
	v_sub_f32_e32 v65, v152, v64
	v_exp_f32_e32 v152, v65
	v_sub_f32_e32 v65, v153, v64
	v_exp_f32_e32 v153, v65
	v_sub_f32_e32 v65, v68, v64
	v_exp_f32_e32 v193, v65
	v_sub_f32_e32 v65, v69, v64
	v_exp_f32_e32 v194, v65
	v_sub_f32_e32 v65, v70, v64
	v_exp_f32_e32 v195, v65
	v_sub_f32_e32 v65, v71, v64
	v_exp_f32_e32 v196, v65
	v_sub_f32_e32 v65, v72, v64
	v_cvt_pk_bf16_f32 v68, v173, v170
	v_cvt_pk_bf16_f32 v69, v171, v172
	v_cvt_pk_bf16_f32 v70, v150, v151
	v_cvt_pk_bf16_f32 v71, v152, v153
	v_exp_f32_e32 v197, v65
	v_sub_f32_e32 v65, v73, v64
	v_mfma_f32_32x32x16_bf16 v[32:47], v[138:141], v[68:71], v[32:47]
	ds_read_b64_tr_b16 v[72:73], v191 offset:18432
	ds_read_b64_tr_b16 v[74:75], v191 offset:20480
	ds_read_b64_tr_b16 v[78:79], v191 offset:20992
	ds_read_b64_tr_b16 v[76:77], v191 offset:18944
	v_exp_f32_e32 v198, v65
	v_sub_f32_e32 v65, v66, v64
	v_sub_f32_e32 v64, v67, v64
	v_cvt_pk_bf16_f32 v66, v197, v198
	v_mfma_f32_32x32x16_bf16 v[48:63], v[146:149], v[68:71], v[48:63]
	v_exp_f32_e32 v146, v65
	v_exp_f32_e32 v147, v64
	v_cvt_pk_bf16_f32 v64, v193, v194
	v_cvt_pk_bf16_f32 v65, v195, v196
	v_cvt_pk_bf16_f32 v67, v146, v147
	s_waitcnt lgkmcnt(2)
	v_mfma_f32_32x32x16_bf16 v[16:31], v[72:75], v[68:71], v[16:31]
	ds_read_b64_tr_b16 v[72:73], v191 offset:22528
	ds_read_b64_tr_b16 v[74:75], v191 offset:24576
	v_mfma_f32_32x32x16_bf16 v[32:47], v[134:137], v[64:67], v[32:47]
	v_add_f32_e32 v134, 0, v173
	v_add_f32_e32 v134, v170, v134
	v_add_f32_e32 v138, v171, v134
	ds_read_b64_tr_b16 v[136:137], v191 offset:25088
	ds_read_b64_tr_b16 v[134:135], v191 offset:23040
	s_waitcnt lgkmcnt(4)
	v_mfma_f32_32x32x16_bf16 v[0:15], v[76:79], v[68:71], v[0:15]
	s_waitcnt lgkmcnt(2)
	v_mfma_f32_32x32x16_bf16 v[16:31], v[72:75], v[64:67], v[16:31]
	v_add_f32_e32 v72, v172, v138
	v_add_f32_e32 v72, v150, v72
	v_add_f32_e32 v72, v151, v72
	v_add_f32_e32 v72, v152, v72
	v_add_f32_e32 v72, v153, v72
	v_add_f32_e32 v72, v193, v72
	v_add_f32_e32 v72, v194, v72
	v_mfma_f32_32x32x16_bf16 v[48:63], v[142:145], v[64:67], v[48:63]
	v_add_f32_e32 v68, v195, v72
	v_add_f32_e32 v68, v196, v68
	v_add_f32_e32 v68, v197, v68
	v_add_f32_e32 v68, v198, v68
	v_add_f32_e32 v68, v146, v68
	v_add_f32_e32 v68, v147, v68
	v_add_f32_e32 v167, v68, v167
	s_waitcnt lgkmcnt(0)
	v_mfma_f32_32x32x16_bf16 v[0:15], v[134:137], v[64:67], v[0:15]

.LBB0_568:
	v_add_u32_e32 v64, 0, v177
	v_add_u32_e32 v136, 0, v162
	s_cmp_lt_i32 s15, 1
	v_mov_b32_e32 v128, v247
	s_cbranch_scc1 .LBB0_597
	v_add_u32_e32 v120, v136, v176
	ds_read_b128 v[64:67], v120
	ds_read_b128 v[112:115], v120 offset:32
	v_or_b32_e32 v134, 32, v159
	v_lshl_add_u32 v135, v134, 2, 0
	s_cmp_gt_u32 s15, 62
	s_waitcnt lgkmcnt(1)
	v_mfma_f32_32x32x16_bf16 v[64:79], v[64:67], v[80:83], 0
	s_mov_b64 s[0:1], -1
	s_cselect_b64 s[4:5], -1, 0
	s_cmp_lt_u32 s15, 63
	s_waitcnt lgkmcnt(0)
	v_mfma_f32_32x32x16_bf16 v[64:79], v[112:115], v[84:87], v[64:79]
	ds_read_b128 v[112:115], v120 offset:64
	ds_read_b128 v[116:119], v120 offset:96
	s_waitcnt lgkmcnt(1)
	v_mfma_f32_32x32x16_bf16 v[64:79], v[112:115], v[88:91], v[64:79]
	s_waitcnt lgkmcnt(0)
	v_mfma_f32_32x32x16_bf16 v[64:79], v[116:119], v[92:95], v[64:79]
	ds_read_b128 v[112:115], v120 offset:128
	ds_read_b128 v[116:119], v120 offset:160
	ds_read_b128 v[130:133], v120 offset:224
	s_waitcnt lgkmcnt(2)
	v_mfma_f32_32x32x16_bf16 v[64:79], v[112:115], v[96:99], v[64:79]
	ds_read_b128 v[112:115], v120 offset:192
	s_waitcnt lgkmcnt(2)
	v_mfma_f32_32x32x16_bf16 v[64:79], v[116:119], v[100:103], v[64:79]
	s_waitcnt lgkmcnt(0)
	v_mfma_f32_32x32x16_bf16 v[64:79], v[112:115], v[104:107], v[64:79]
	ds_read_b64_tr_b16 v[124:125], v128 offset:25600
	ds_read_b64_tr_b16 v[126:127], v128 offset:27648
	ds_read_b64_tr_b16 v[114:115], v128 offset:28160
	ds_read_b64_tr_b16 v[112:113], v128 offset:26112
	ds_read_b64_tr_b16 v[120:121], v128 offset:29696
	ds_read_b64_tr_b16 v[122:123], v128 offset:31744
	ds_read_b64_tr_b16 v[118:119], v128 offset:32256
	ds_read_b64_tr_b16 v[116:117], v128 offset:30208
	ds_read_b128 v[138:141], v135 offset:34816
	v_mfma_f32_32x32x16_bf16 v[64:79], v[130:133], v[108:111], v[64:79]
	s_waitcnt lgkmcnt(0)
	v_xor_b32_e32 v133, 0x80000000, v140
	v_xor_b32_e32 v132, 0x80000000, v139
	s_nop 8
	v_sub_f32_e32 v139, v64, v138
	v_sub_f32_e32 v138, v67, v141
	s_cbranch_scc1 .LBB0_571
	v_mov_b32_e32 v130, v65
	v_mov_b32_e32 v131, v66
	v_pk_add_f32 v[130:131], v[130:131], v[132:133]
	s_mov_b64 s[0:1], 0
	v_max3_f32 v64, v139, s87, v130
	v_max3_f32 v137, v64, v131, v138

.LBB0_587:
	v_sub_f32_e32 v65, v139, v64
	v_exp_f32_e32 v139, v65
	v_sub_f32_e32 v65, v130, v64
	v_exp_f32_e32 v130, v65
	v_sub_f32_e32 v65, v131, v64
	v_exp_f32_e32 v131, v65
	v_sub_f32_e32 v65, v138, v64
	v_exp_f32_e32 v138, v65
	v_sub_f32_e32 v65, v132, v64
	v_exp_f32_e32 v132, v65
	v_sub_f32_e32 v65, v133, v64
	v_exp_f32_e32 v133, v65
	v_sub_f32_e32 v65, v134, v64
	v_exp_f32_e32 v134, v65
	v_sub_f32_e32 v65, v135, v64
	v_exp_f32_e32 v135, v65
	v_sub_f32_e32 v65, v68, v64
	v_exp_f32_e32 v140, v65
	v_sub_f32_e32 v65, v69, v64
	v_exp_f32_e32 v141, v65
	v_sub_f32_e32 v65, v70, v64
	v_exp_f32_e32 v142, v65
	v_sub_f32_e32 v65, v71, v64
	v_cvt_pk_bf16_f32 v68, v139, v130
	v_cvt_pk_bf16_f32 v69, v131, v138
	v_cvt_pk_bf16_f32 v70, v132, v133
	v_cvt_pk_bf16_f32 v71, v134, v135
	v_exp_f32_e32 v143, v65
	v_sub_f32_e32 v65, v72, v64
	v_mfma_f32_32x32x16_bf16 v[32:47], v[112:115], v[68:71], v[32:47]
	v_exp_f32_e32 v144, v65
	v_sub_f32_e32 v65, v73, v64
	v_exp_f32_e32 v145, v65
	v_sub_f32_e32 v65, v66, v64
	v_sub_f32_e32 v64, v67, v64
	ds_read_b64_tr_b16 v[72:73], v128 offset:26624
	v_cvt_pk_bf16_f32 v66, v144, v145
	v_mfma_f32_32x32x16_bf16 v[48:63], v[124:127], v[68:71], v[48:63]
	v_exp_f32_e32 v124, v65
	v_exp_f32_e32 v125, v64
	v_cvt_pk_bf16_f32 v64, v140, v141
	v_cvt_pk_bf16_f32 v65, v142, v143
	v_cvt_pk_bf16_f32 v67, v124, v125
	s_nop 1
	v_mfma_f32_32x32x16_bf16 v[32:47], v[116:119], v[64:67], v[32:47]
	ds_read_b64_tr_b16 v[74:75], v128 offset:28672
	ds_read_b64_tr_b16 v[76:77], v128 offset:30720
	ds_read_b64_tr_b16 v[112:113], v128 offset:31232
	ds_read_b64_tr_b16 v[118:119], v128 offset:29184
	ds_read_b64_tr_b16 v[116:117], v128 offset:27136
	ds_read_b64_tr_b16 v[114:115], v128 offset:33280
	ds_read_b64_tr_b16 v[78:79], v128 offset:32768
	s_waitcnt lgkmcnt(6)
	v_mfma_f32_32x32x16_bf16 v[16:31], v[72:75], v[68:71], v[16:31]
	v_add_f32_e32 v72, 0, v139
	v_add_f32_e32 v72, v130, v72
	v_add_f32_e32 v72, v131, v72
	v_add_f32_e32 v72, v138, v72
	v_add_f32_e32 v72, v132, v72
	v_add_f32_e32 v72, v133, v72
	v_add_f32_e32 v72, v134, v72
	s_waitcnt lgkmcnt(2)
	v_mfma_f32_32x32x16_bf16 v[0:15], v[116:119], v[68:71], v[0:15]
	v_add_f32_e32 v72, v135, v72
	v_add_f32_e32 v72, v140, v72
	v_add_f32_e32 v72, v141, v72
	v_add_f32_e32 v68, v142, v72
	v_add_f32_e32 v68, v143, v68
	v_add_f32_e32 v68, v144, v68
	v_add_f32_e32 v68, v145, v68
	v_mfma_f32_32x32x16_bf16 v[48:63], v[120:123], v[64:67], v[48:63]
	v_add_f32_e32 v68, v124, v68
	v_add_f32_e32 v68, v125, v68
	v_add_f32_e32 v167, v68, v167
	s_waitcnt lgkmcnt(0)
	v_mfma_f32_32x32x16_bf16 v[16:31], v[76:79], v[64:67], v[16:31]
	v_mfma_f32_32x32x16_bf16 v[0:15], v[112:115], v[64:67], v[0:15]
	s_cmpk_lt_i32 s15, 0xffe1
	s_cbranch_scc0 .LBB0_598
	s_branch .LBB0_617

.LBB0_598:
	v_add_u32_e32 v116, v136, v169
	ds_read_b128 v[64:67], v116
	ds_read_b128 v[112:115], v116 offset:32
	s_cmp_gt_i32 s15, 30
	s_mov_b64 s[0:1], -1
	s_cselect_b64 s[4:5], -1, 0
	s_waitcnt lgkmcnt(1)
	v_mfma_f32_32x32x16_bf16 v[64:79], v[64:67], v[80:83], 0
	s_cmp_lt_i32 s15, 31
	s_waitcnt lgkmcnt(0)
	v_mfma_f32_32x32x16_bf16 v[64:79], v[112:115], v[84:87], v[64:79]
	ds_read_b128 v[80:83], v116 offset:64
	ds_read_b128 v[84:87], v116 offset:96
	s_waitcnt lgkmcnt(1)
	v_mfma_f32_32x32x16_bf16 v[64:79], v[80:83], v[88:91], v[64:79]
	s_waitcnt lgkmcnt(0)
	v_mfma_f32_32x32x16_bf16 v[64:79], v[84:87], v[92:95], v[64:79]
	ds_read_b128 v[80:83], v116 offset:128
	ds_read_b128 v[84:87], v116 offset:160
	s_waitcnt lgkmcnt(1)
	v_mfma_f32_32x32x16_bf16 v[64:79], v[80:83], v[96:99], v[64:79]
	ds_read_b128 v[80:83], v116 offset:192
	ds_read_b128 v[96:99], v116 offset:224
	s_waitcnt lgkmcnt(2)
	v_mfma_f32_32x32x16_bf16 v[64:79], v[84:87], v[100:103], v[64:79]
	s_waitcnt lgkmcnt(1)
	v_mfma_f32_32x32x16_bf16 v[64:79], v[80:83], v[104:107], v[64:79]
	ds_read_b64_tr_b16 v[92:93], v128 offset:17408
	ds_read_b64_tr_b16 v[94:95], v128 offset:19456
	ds_read_b64_tr_b16 v[82:83], v128 offset:19968
	ds_read_b64_tr_b16 v[80:81], v128 offset:17920
	ds_read_b64_tr_b16 v[88:89], v128 offset:21504
	ds_read_b64_tr_b16 v[90:91], v128 offset:23552
	ds_read_b64_tr_b16 v[86:87], v128 offset:24064
	ds_read_b64_tr_b16 v[84:85], v128 offset:22016
	s_waitcnt lgkmcnt(8)
	v_mfma_f32_32x32x16_bf16 v[64:79], v[96:99], v[108:111], v[64:79]
	ds_read_b128 v[96:99], v136 offset:34816
	s_waitcnt lgkmcnt(0)
	v_xor_b32_e32 v103, 0x80000000, v98
	s_nop 8
	v_sub_f32_e32 v96, v64, v96
	s_cbranch_scc1 .LBB0_600
	v_mov_b32_e32 v100, v65
	v_mov_b32_e32 v101, v66
	v_xor_b32_e32 v102, 0x80000000, v97
	v_pk_add_f32 v[100:101], v[100:101], v[102:103]
	v_sub_f32_e32 v98, v67, v99
	v_max3_f32 v64, v96, s87, v100
	v_max3_f32 v102, v64, v101, v98
	s_mov_b64 s[0:1], 0

.LBB0_616:
	v_sub_f32_e32 v71, v96, v70
	v_sub_f32_e32 v64, v64, v70
	v_exp_f32_e32 v96, v71
	v_sub_f32_e32 v71, v100, v70
	v_exp_f32_e32 v103, v64
	v_sub_f32_e32 v64, v65, v70
	v_exp_f32_e32 v100, v71
	v_sub_f32_e32 v71, v101, v70
	v_exp_f32_e32 v104, v64
	v_sub_f32_e32 v64, v97, v70
	v_exp_f32_e32 v101, v71
	v_sub_f32_e32 v71, v98, v70
	v_exp_f32_e32 v97, v64
	v_sub_f32_e32 v64, v102, v70
	v_exp_f32_e32 v98, v71
	v_sub_f32_e32 v71, v99, v70
	v_exp_f32_e32 v102, v64
	v_sub_f32_e32 v64, v66, v70
	v_exp_f32_e32 v99, v71
	v_exp_f32_e32 v105, v64
	v_sub_f32_e32 v64, v67, v70
	v_exp_f32_e32 v106, v64
	v_sub_f32_e32 v64, v72, v70
	v_exp_f32_e32 v107, v64
	v_sub_f32_e32 v64, v74, v70
	v_exp_f32_e32 v108, v64
	v_sub_f32_e32 v64, v68, v70
	v_exp_f32_e32 v109, v64
	v_sub_f32_e32 v68, v69, v70
	v_cvt_pk_bf16_f32 v64, v96, v100
	v_cvt_pk_bf16_f32 v65, v101, v98
	v_cvt_pk_bf16_f32 v66, v99, v103
	v_cvt_pk_bf16_f32 v67, v104, v97
	v_cvt_pk_bf16_f32 v69, v106, v107
	s_nop 0
	v_mfma_f32_32x32x16_bf16 v[48:63], v[92:95], v[64:67], v[48:63]
	v_exp_f32_e32 v92, v68
	v_sub_f32_e32 v68, v73, v70
	ds_read_b64_tr_b16 v[72:73], v128 offset:18432
	ds_read_b64_tr_b16 v[74:75], v128 offset:20480
	ds_read_b64_tr_b16 v[78:79], v128 offset:20992
	ds_read_b64_tr_b16 v[76:77], v128 offset:18944
	v_exp_f32_e32 v93, v68
	v_cvt_pk_bf16_f32 v68, v102, v105
	v_cvt_pk_bf16_f32 v70, v108, v109
	v_cvt_pk_bf16_f32 v71, v92, v93
	v_mfma_f32_32x32x16_bf16 v[32:47], v[80:83], v[64:67], v[32:47]
	v_add_f32_e32 v80, 0, v96
	v_add_f32_e32 v80, v100, v80
	s_waitcnt lgkmcnt(2)
	v_mfma_f32_32x32x16_bf16 v[16:31], v[72:75], v[64:67], v[16:31]
	ds_read_b64_tr_b16 v[72:73], v128 offset:22528
	ds_read_b64_tr_b16 v[74:75], v128 offset:24576
	s_waitcnt lgkmcnt(2)
	v_mfma_f32_32x32x16_bf16 v[0:15], v[76:79], v[64:67], v[0:15]
	v_mfma_f32_32x32x16_bf16 v[32:47], v[84:87], v[68:71], v[32:47]
	v_add_f32_e32 v84, v101, v80
	ds_read_b64_tr_b16 v[82:83], v128 offset:25088
	ds_read_b64_tr_b16 v[80:81], v128 offset:23040
	s_waitcnt lgkmcnt(2)
	v_mfma_f32_32x32x16_bf16 v[16:31], v[72:75], v[68:71], v[16:31]
	v_add_f32_e32 v72, v98, v84
	v_add_f32_e32 v72, v99, v72
	v_add_f32_e32 v72, v103, v72
	v_add_f32_e32 v72, v104, v72
	v_add_f32_e32 v72, v97, v72
	v_add_f32_e32 v72, v102, v72
	v_add_f32_e32 v72, v105, v72
	v_mfma_f32_32x32x16_bf16 v[48:63], v[88:91], v[68:71], v[48:63]
	v_add_f32_e32 v64, v106, v72
	v_add_f32_e32 v64, v107, v64
	v_add_f32_e32 v64, v108, v64
	v_add_f32_e32 v64, v109, v64
	v_add_f32_e32 v64, v92, v64
	v_add_f32_e32 v64, v93, v64
	v_add_f32_e32 v167, v64, v167
	s_waitcnt lgkmcnt(0)
	v_mfma_f32_32x32x16_bf16 v[0:15], v[80:83], v[68:71], v[0:15]
